# X38: all four GEMM K-loops - LDS-DMA loads with scalar base + 32-bit lane offset (and instruction offset for the second K half) instead of per-load 64-bit vector adds, B-fragment LDS read addresses ho
# speedup vs baseline: 1.0038x; 1.0018x over previous
; #define PG8_STAGE(bufoff, gbase, voff) do { _Pragma("unroll") for (int _i = 0; _i < 2; ++_i) \
;         __builtin_amdgcn_global_load_lds((const unsigned*)((const char*)(gbase) + (voff)[_i]), (PG8_LAS unsigned*)(lds + (bufoff) + ldsw + _i * 8192), 16, 0, 0); } while (0)
; #define PG8_LDA(dst, b, h) do { _Pragma("unroll") for (int m = 0; m < 4; ++m) _Pragma("unroll") for (int k = 0; k < 2; ++k) dst[m][k] = *(const PG8_LAS bf16x8*)(lds + PG8_SA(b, h) + aoff + m * 2048 + k * 1024); } while (0)
; #define PG8_LDB(dst, b, h) do { _Pragma("unroll") for (int n = 0; n < 2; ++n) _Pragma("unroll") for (int k = 0; k < 2; ++k) dst[n][k] = *(const PG8_LAS bf16x8*)(lds + PG8_SB(b, h) + boff + n * 2048 + k * 1024); } while (0)
; #define PG8_MMA(ai, bj, At, Bt) do { __builtin_amdgcn_s_setprio(1); _Pragma("unroll") for (int m = 0; m < 4; ++m) _Pragma("unroll") for (int n = 0; n < 2; ++n) _Pragma("unroll") for (int k = 0; k < 2; ++k) \
;         acc[ai][bj][m][n] = __builtin_amdgcn_mfma_f32_16x16x32_bf16(Bt[n][k], At[m][k], acc[ai][bj][m][n], 0, 0, 0); __builtin_amdgcn_s_setprio(0); } while (0)
; #define PG8_WAIT_V(n) asm volatile("s_waitcnt vmcnt(" #n ")" ::: "memory")
; #define PG8_WAIT_L(n) asm volatile("s_waitcnt lgkmcnt(" #n ")" ::: "memory")
; #define PG8_BAR __builtin_amdgcn_s_barrier()
; #define PG8_SCHED __builtin_amdgcn_sched_barrier(0)
; template <class Epi, class Sched, bool ALIGN_EPI = false, bool SP2 = false>
; __device__ __forceinline__ void gemm_phase(PG8_LAS unsigned char* lds, const Gemm g, const Sched& S, const Epi& E) {
;     ...
;         for (int t = 0; t < nt; t += 2) {
;             const bool last = (t == nt - 2);
;             const char* a1 = cA + (size_t)(t + 1) * kstep;
;             const char* a2 = last ? nA : cA + (size_t)(t + 2) * kstep; const char* b2 = last ? nB : cB + (size_t)(t + 2) * kstep;
;             const char* a3 = a2 + kstep; const char* b3 = b2 + kstep;
;             if (last && has_next) S.a_ready(nxt);
;             if constexpr (SP2) {
;             PG8_LDB(B0, 0, 0); PG8_LDB(B1, 0, 1); PG8_SCHED; PG8_LDA(At, 0, 0); PG8_STAGE(PG8_SA(1, 1), a1 + hstep, voffA);
;             PG8_WAIT_V(8); PG8_WAIT_L(0); PG8_BAR; PG8_MMA(0, 0, At, B0); PG8_MMA(0, 1, At, B1); PG8_BAR; PG8_SCHED;
;             PG8_LDA(At, 0, 1); PG8_STAGE(PG8_SB(0, 0), b2, voffB); PG8_STAGE(PG8_SB(0, 1), b2 + hstep, voffB); PG8_STAGE(PG8_SA(0, 0), a2, voffA);
.LBB0_298:
	s_add_u32 s33, s50, 0x100
	s_addc_u32 s69, s51, 0
	s_mov_b32 s20, -2
	v_add_u32_e32 v238, 0x10000, v158
	v_add_u32_e32 v239, 0x14000, v158
	v_add_u32_e32 v240, 0x18000, v158
	v_add_u32_e32 v241, 0x1c000, v158
.LBB0_299:
	s_add_u32 s50, s22, 0x100
	s_addc_u32 s51, s23, 0
	s_add_i32 s4, 0, 0x10000
	s_cmpk_eq_i32 s20, 0x54
	s_cselect_b32 s55, s41, s51
	s_cselect_b32 s54, s40, s50
	s_cselect_b32 s53, s49, s69
	s_cselect_b32 s52, s48, s33
	s_add_i32 s5, 0, 0x14000
	ds_read_b128 v[134:137], v238
	ds_read_b128 v[138:141], v238 offset:1024
	ds_read_b128 v[142:145], v238 offset:2048
	ds_read_b128 v[146:149], v238 offset:3072
	ds_read_b128 v[150:153], v239
	ds_read_b128 v[154:157], v239 offset:1024
	ds_read_b128 v[176:179], v239 offset:2048
	ds_read_b128 v[180:183], v239 offset:3072
	v_lshl_add_u64 v[236:237], s[22:23], 0, v[172:173]
	s_add_i32 m0, s56, 0xc000
	ds_read_b128 v[184:187], v188
	ds_read_b128 v[190:193], v188 offset:1024
	ds_read_b128 v[212:215], v188 offset:2048
	ds_read_b128 v[216:219], v188 offset:3072
	ds_read_b128 v[220:223], v188 offset:4096
	ds_read_b128 v[224:227], v188 offset:5120
	ds_read_b128 v[228:231], v188 offset:6144
	ds_read_b128 v[232:235], v188 offset:7168
	global_load_lds_dwordx4 v[236:237], off
	v_lshl_add_u64 v[236:237], s[22:23], 0, v[174:175]
	s_add_i32 m0, s56, 0xe000
	s_nop 0
	global_load_lds_dwordx4 v[236:237], off
	s_waitcnt vmcnt(8)
	s_waitcnt lgkmcnt(0)
	s_barrier
	v_mfma_f32_16x16x32_bf16 v[122:125], v[134:137], v[184:187], v[122:125]
	v_mfma_f32_16x16x32_bf16 v[122:125], v[138:141], v[190:193], v[122:125]
	v_mfma_f32_16x16x32_bf16 v[118:121], v[142:145], v[184:187], v[118:121]
	v_mfma_f32_16x16x32_bf16 v[118:121], v[146:149], v[190:193], v[118:121]
	v_mfma_f32_16x16x32_bf16 v[130:133], v[150:153], v[184:187], v[130:133]
	v_mfma_f32_16x16x32_bf16 v[130:133], v[154:157], v[190:193], v[130:133]
	v_mfma_f32_16x16x32_bf16 v[126:129], v[176:179], v[184:187], v[126:129]
	v_mfma_f32_16x16x32_bf16 v[126:129], v[180:183], v[190:193], v[126:129]
	v_mfma_f32_16x16x32_bf16 v[102:105], v[176:179], v[212:215], v[102:105]
	v_mfma_f32_16x16x32_bf16 v[102:105], v[180:183], v[216:219], v[102:105]
	v_mfma_f32_16x16x32_bf16 v[106:109], v[150:153], v[212:215], v[106:109]
	v_mfma_f32_16x16x32_bf16 v[106:109], v[154:157], v[216:219], v[106:109]
	v_mfma_f32_16x16x32_bf16 v[110:113], v[142:145], v[212:215], v[110:113]
	v_mfma_f32_16x16x32_bf16 v[110:113], v[146:149], v[216:219], v[110:113]
	v_mfma_f32_16x16x32_bf16 v[114:117], v[134:137], v[212:215], v[114:117]
	v_mfma_f32_16x16x32_bf16 v[114:117], v[138:141], v[216:219], v[114:117]
	v_mfma_f32_16x16x32_bf16 v[98:101], v[134:137], v[220:223], v[98:101]
	v_mfma_f32_16x16x32_bf16 v[98:101], v[138:141], v[224:227], v[98:101]
	v_mfma_f32_16x16x32_bf16 v[94:97], v[142:145], v[220:223], v[94:97]
	v_mfma_f32_16x16x32_bf16 v[94:97], v[146:149], v[224:227], v[94:97]
	v_mfma_f32_16x16x32_bf16 v[90:93], v[150:153], v[220:223], v[90:93]
	v_mfma_f32_16x16x32_bf16 v[90:93], v[154:157], v[224:227], v[90:93]
	v_mfma_f32_16x16x32_bf16 v[86:89], v[176:179], v[220:223], v[86:89]
	v_mfma_f32_16x16x32_bf16 v[86:89], v[180:183], v[224:227], v[86:89]
	v_mfma_f32_16x16x32_bf16 v[70:73], v[176:179], v[228:231], v[70:73]
	v_mfma_f32_16x16x32_bf16 v[70:73], v[180:183], v[232:235], v[70:73]
	v_mfma_f32_16x16x32_bf16 v[74:77], v[150:153], v[228:231], v[74:77]
	v_mfma_f32_16x16x32_bf16 v[74:77], v[154:157], v[232:235], v[74:77]
	v_mfma_f32_16x16x32_bf16 v[78:81], v[142:145], v[228:231], v[78:81]
	v_mfma_f32_16x16x32_bf16 v[78:81], v[146:149], v[232:235], v[78:81]
	v_mfma_f32_16x16x32_bf16 v[82:85], v[134:137], v[228:231], v[82:85]
	v_mfma_f32_16x16x32_bf16 v[82:85], v[138:141], v[232:235], v[82:85]
	s_barrier
	s_add_i32 s4, s4, s24
	s_mov_b32 m0, s4
	ds_read_b128 v[184:187], v188 offset:16384
	ds_read_b128 v[190:193], v188 offset:17408
	ds_read_b128 v[212:215], v188 offset:18432
	ds_read_b128 v[216:219], v188 offset:19456
	ds_read_b128 v[220:223], v188 offset:20480
	ds_read_b128 v[224:227], v188 offset:21504
	ds_read_b128 v[228:231], v188 offset:22528
	ds_read_b128 v[232:235], v188 offset:23552
	global_load_lds_dwordx4 v4, s[52:53]
	s_add_i32 m0, s4, 0x2000
	s_add_u32 s22, s52, 0x160000
	s_addc_u32 s23, s53, 0
	s_add_i32 s4, s5, s24
	global_load_lds_dwordx4 v170, s[52:53]
	s_mov_b32 m0, s4
	s_nop 0
	global_load_lds_dwordx4 v4, s[22:23]
	s_add_i32 m0, s4, 0x2000
	s_nop 0
	global_load_lds_dwordx4 v170, s[22:23]
	s_mov_b32 m0, s56
	s_nop 0
	global_load_lds_dwordx4 v2, s[54:55]
	s_mov_b32 m0, s57
	s_nop 0
	global_load_lds_dwordx4 v168, s[54:55]
	s_waitcnt vmcnt(8)
	s_waitcnt lgkmcnt(0)
	s_barrier
; #define PG8_STAGE(bufoff, gbase, voff) do { _Pragma("unroll") for (int _i = 0; _i < 2; ++_i) \
;         __builtin_amdgcn_global_load_lds((const unsigned*)((const char*)(gbase) + (voff)[_i]), (PG8_LAS unsigned*)(lds + (bufoff) + ldsw + _i * 8192), 16, 0, 0); } while (0)
; #define PG8_LDA(dst, b, h) do { _Pragma("unroll") for (int m = 0; m < 4; ++m) _Pragma("unroll") for (int k = 0; k < 2; ++k) dst[m][k] = *(const PG8_LAS bf16x8*)(lds + PG8_SA(b, h) + aoff + m * 2048 + k * 1024); } while (0)
; #define PG8_LDB(dst, b, h) do { _Pragma("unroll") for (int n = 0; n < 2; ++n) _Pragma("unroll") for (int k = 0; k < 2; ++k) dst[n][k] = *(const PG8_LAS bf16x8*)(lds + PG8_SB(b, h) + boff + n * 2048 + k * 1024); } while (0)
; #define PG8_MMA(ai, bj, At, Bt) do { __builtin_amdgcn_s_setprio(1); _Pragma("unroll") for (int m = 0; m < 4; ++m) _Pragma("unroll") for (int n = 0; n < 2; ++n) _Pragma("unroll") for (int k = 0; k < 2; ++k) \
;         acc[ai][bj][m][n] = __builtin_amdgcn_mfma_f32_16x16x32_bf16(Bt[n][k], At[m][k], acc[ai][bj][m][n], 0, 0, 0); __builtin_amdgcn_s_setprio(0); } while (0)
; #define PG8_WAIT_V(n) asm volatile("s_waitcnt vmcnt(" #n ")" ::: "memory")
; #define PG8_WAIT_L(n) asm volatile("s_waitcnt lgkmcnt(" #n ")" ::: "memory")
; #define PG8_BAR __builtin_amdgcn_s_barrier()
; #define PG8_SCHED __builtin_amdgcn_sched_barrier(0)
; template <class Epi, class Sched, bool ALIGN_EPI = false, bool SP2 = false>
; __device__ __forceinline__ void gemm_phase(PG8_LAS unsigned char* lds, const Gemm g, const Sched& S, const Epi& E) {
;     ...
;             PG8_WAIT_V(8); PG8_WAIT_L(0); PG8_BAR; PG8_MMA(1, 0, At, B0); PG8_MMA(1, 1, At, B1); PG8_BAR; PG8_SCHED;
;             PG8_LDB(B0, 1, 0); PG8_LDB(B1, 1, 1); PG8_SCHED; PG8_LDA(At, 1, 0); PG8_STAGE(PG8_SA(0, 1), a2 + hstep, voffA);
;             PG8_WAIT_V(8); PG8_WAIT_L(0); PG8_BAR; PG8_MMA(0, 0, At, B0); PG8_MMA(0, 1, At, B1); PG8_BAR; PG8_SCHED;
	v_mfma_f32_16x16x32_bf16 v[58:61], v[134:137], v[184:187], v[58:61]
	v_mfma_f32_16x16x32_bf16 v[58:61], v[138:141], v[190:193], v[58:61]
	v_mfma_f32_16x16x32_bf16 v[54:57], v[142:145], v[184:187], v[54:57]
	v_mfma_f32_16x16x32_bf16 v[54:57], v[146:149], v[190:193], v[54:57]
	v_mfma_f32_16x16x32_bf16 v[66:69], v[150:153], v[184:187], v[66:69]
	v_mfma_f32_16x16x32_bf16 v[66:69], v[154:157], v[190:193], v[66:69]
	v_mfma_f32_16x16x32_bf16 v[62:65], v[176:179], v[184:187], v[62:65]
	v_mfma_f32_16x16x32_bf16 v[62:65], v[180:183], v[190:193], v[62:65]
	v_mfma_f32_16x16x32_bf16 v[38:41], v[176:179], v[212:215], v[38:41]
	v_mfma_f32_16x16x32_bf16 v[38:41], v[180:183], v[216:219], v[38:41]
	v_mfma_f32_16x16x32_bf16 v[42:45], v[150:153], v[212:215], v[42:45]
	v_mfma_f32_16x16x32_bf16 v[42:45], v[154:157], v[216:219], v[42:45]
	v_mfma_f32_16x16x32_bf16 v[46:49], v[142:145], v[212:215], v[46:49]
	v_mfma_f32_16x16x32_bf16 v[46:49], v[146:149], v[216:219], v[46:49]
	v_mfma_f32_16x16x32_bf16 v[50:53], v[134:137], v[212:215], v[50:53]
	v_mfma_f32_16x16x32_bf16 v[50:53], v[138:141], v[216:219], v[50:53]
	v_mfma_f32_16x16x32_bf16 v[34:37], v[134:137], v[220:223], v[34:37]
	v_mfma_f32_16x16x32_bf16 v[34:37], v[138:141], v[224:227], v[34:37]
	v_mfma_f32_16x16x32_bf16 v[30:33], v[142:145], v[220:223], v[30:33]
	v_mfma_f32_16x16x32_bf16 v[30:33], v[146:149], v[224:227], v[30:33]
	v_mfma_f32_16x16x32_bf16 v[26:29], v[150:153], v[220:223], v[26:29]
	v_mfma_f32_16x16x32_bf16 v[26:29], v[154:157], v[224:227], v[26:29]
	v_mfma_f32_16x16x32_bf16 v[22:25], v[176:179], v[220:223], v[22:25]
	v_mfma_f32_16x16x32_bf16 v[22:25], v[180:183], v[224:227], v[22:25]
	v_mfma_f32_16x16x32_bf16 v[6:9], v[176:179], v[228:231], v[6:9]
	v_mfma_f32_16x16x32_bf16 v[6:9], v[180:183], v[232:235], v[6:9]
	v_mfma_f32_16x16x32_bf16 v[10:13], v[150:153], v[228:231], v[10:13]
	v_mfma_f32_16x16x32_bf16 v[10:13], v[154:157], v[232:235], v[10:13]
	v_mfma_f32_16x16x32_bf16 v[14:17], v[142:145], v[228:231], v[14:17]
	v_mfma_f32_16x16x32_bf16 v[14:17], v[146:149], v[232:235], v[14:17]
	v_mfma_f32_16x16x32_bf16 v[18:21], v[134:137], v[228:231], v[18:21]
	v_mfma_f32_16x16x32_bf16 v[18:21], v[138:141], v[232:235], v[18:21]
	s_barrier
	s_add_i32 s4, 0, 0x18000
	s_add_i32 s5, 0, 0x1c000
	ds_read_b128 v[134:137], v240
	ds_read_b128 v[138:141], v240 offset:1024
	ds_read_b128 v[142:145], v240 offset:2048
	ds_read_b128 v[146:149], v240 offset:3072
	ds_read_b128 v[150:153], v241
	ds_read_b128 v[154:157], v241 offset:1024
	ds_read_b128 v[176:179], v241 offset:2048
	ds_read_b128 v[180:183], v241 offset:3072
	s_add_u32 s22, s54, 0x160000
	s_addc_u32 s23, s55, 0
	s_mov_b32 m0, s59
	ds_read_b128 v[184:187], v188 offset:32768
	ds_read_b128 v[190:193], v188 offset:33792
	ds_read_b128 v[212:215], v188 offset:34816
	ds_read_b128 v[216:219], v188 offset:35840
	ds_read_b128 v[220:223], v188 offset:36864
	ds_read_b128 v[224:227], v188 offset:37888
	ds_read_b128 v[228:231], v188 offset:38912
	ds_read_b128 v[232:235], v188 offset:39936
	global_load_lds_dwordx4 v2, s[22:23]
	s_mov_b32 m0, s60
	s_nop 0
	global_load_lds_dwordx4 v168, s[22:23]
	s_waitcnt vmcnt(8)
	s_waitcnt lgkmcnt(0)
	s_barrier
	v_mfma_f32_16x16x32_bf16 v[122:125], v[134:137], v[184:187], v[122:125]
	v_mfma_f32_16x16x32_bf16 v[122:125], v[138:141], v[190:193], v[122:125]
	v_mfma_f32_16x16x32_bf16 v[118:121], v[142:145], v[184:187], v[118:121]
	v_mfma_f32_16x16x32_bf16 v[118:121], v[146:149], v[190:193], v[118:121]
	v_mfma_f32_16x16x32_bf16 v[130:133], v[150:153], v[184:187], v[130:133]
	v_mfma_f32_16x16x32_bf16 v[130:133], v[154:157], v[190:193], v[130:133]
	v_mfma_f32_16x16x32_bf16 v[126:129], v[176:179], v[184:187], v[126:129]
	v_mfma_f32_16x16x32_bf16 v[126:129], v[180:183], v[190:193], v[126:129]
	v_mfma_f32_16x16x32_bf16 v[102:105], v[176:179], v[212:215], v[102:105]
	v_mfma_f32_16x16x32_bf16 v[102:105], v[180:183], v[216:219], v[102:105]
	v_mfma_f32_16x16x32_bf16 v[106:109], v[150:153], v[212:215], v[106:109]
	v_mfma_f32_16x16x32_bf16 v[106:109], v[154:157], v[216:219], v[106:109]
	v_mfma_f32_16x16x32_bf16 v[110:113], v[142:145], v[212:215], v[110:113]
	v_mfma_f32_16x16x32_bf16 v[110:113], v[146:149], v[216:219], v[110:113]
	v_mfma_f32_16x16x32_bf16 v[114:117], v[134:137], v[212:215], v[114:117]
	v_mfma_f32_16x16x32_bf16 v[114:117], v[138:141], v[216:219], v[114:117]
	v_mfma_f32_16x16x32_bf16 v[98:101], v[134:137], v[220:223], v[98:101]
	v_mfma_f32_16x16x32_bf16 v[98:101], v[138:141], v[224:227], v[98:101]
	v_mfma_f32_16x16x32_bf16 v[94:97], v[142:145], v[220:223], v[94:97]
	v_mfma_f32_16x16x32_bf16 v[94:97], v[146:149], v[224:227], v[94:97]
	v_mfma_f32_16x16x32_bf16 v[90:93], v[150:153], v[220:223], v[90:93]
	v_mfma_f32_16x16x32_bf16 v[90:93], v[154:157], v[224:227], v[90:93]
	v_mfma_f32_16x16x32_bf16 v[86:89], v[176:179], v[220:223], v[86:89]
	v_mfma_f32_16x16x32_bf16 v[86:89], v[180:183], v[224:227], v[86:89]
	v_mfma_f32_16x16x32_bf16 v[70:73], v[176:179], v[228:231], v[70:73]
	v_mfma_f32_16x16x32_bf16 v[70:73], v[180:183], v[232:235], v[70:73]
	v_mfma_f32_16x16x32_bf16 v[74:77], v[150:153], v[228:231], v[74:77]
	v_mfma_f32_16x16x32_bf16 v[74:77], v[154:157], v[232:235], v[74:77]
	v_mfma_f32_16x16x32_bf16 v[78:81], v[142:145], v[228:231], v[78:81]
	v_mfma_f32_16x16x32_bf16 v[78:81], v[146:149], v[232:235], v[78:81]
	v_mfma_f32_16x16x32_bf16 v[82:85], v[134:137], v[228:231], v[82:85]
	v_mfma_f32_16x16x32_bf16 v[82:85], v[138:141], v[232:235], v[82:85]
	s_barrier
; #define PG8_STAGE(bufoff, gbase, voff) do { _Pragma("unroll") for (int _i = 0; _i < 2; ++_i) \
;         __builtin_amdgcn_global_load_lds((const unsigned*)((const char*)(gbase) + (voff)[_i]), (PG8_LAS unsigned*)(lds + (bufoff) + ldsw + _i * 8192), 16, 0, 0); } while (0)
; #define PG8_LDA(dst, b, h) do { _Pragma("unroll") for (int m = 0; m < 4; ++m) _Pragma("unroll") for (int k = 0; k < 2; ++k) dst[m][k] = *(const PG8_LAS bf16x8*)(lds + PG8_SA(b, h) + aoff + m * 2048 + k * 1024); } while (0)
; #define PG8_MMA(ai, bj, At, Bt) do { __builtin_amdgcn_s_setprio(1); _Pragma("unroll") for (int m = 0; m < 4; ++m) _Pragma("unroll") for (int n = 0; n < 2; ++n) _Pragma("unroll") for (int k = 0; k < 2; ++k) \
;         acc[ai][bj][m][n] = __builtin_amdgcn_mfma_f32_16x16x32_bf16(Bt[n][k], At[m][k], acc[ai][bj][m][n], 0, 0, 0); __builtin_amdgcn_s_setprio(0); } while (0)
; #define PG8_WAIT_V(n) asm volatile("s_waitcnt vmcnt(" #n ")" ::: "memory")
; #define PG8_WAIT_L(n) asm volatile("s_waitcnt lgkmcnt(" #n ")" ::: "memory")
; #define PG8_BAR __builtin_amdgcn_s_barrier()
; #define PG8_SCHED __builtin_amdgcn_sched_barrier(0)
; template <class Epi, class Sched, bool ALIGN_EPI = false, bool SP2 = false>
; __device__ __forceinline__ void gemm_phase(PG8_LAS unsigned char* lds, const Gemm g, const Sched& S, const Epi& E) {
;     ...
;         for (int t = 0; t < nt; t += 2) {
;     ...
;             PG8_LDA(At, 1, 1); PG8_STAGE(PG8_SB(1, 0), b3, voffB); PG8_STAGE(PG8_SB(1, 1), b3 + hstep, voffB); PG8_STAGE(PG8_SA(1, 0), a3, voffA);
;             PG8_WAIT_V(8); PG8_WAIT_L(0); PG8_BAR; PG8_MMA(1, 0, At, B0); PG8_MMA(1, 1, At, B1); PG8_BAR; PG8_SCHED;
	s_add_i32 s4, s4, s24
	s_add_i32 m0, s4, 0xffffff80
	ds_read_b128 v[184:187], v188 offset:49152
	ds_read_b128 v[190:193], v188 offset:50176
	ds_read_b128 v[212:215], v188 offset:51200
	ds_read_b128 v[216:219], v188 offset:52224
	ds_read_b128 v[220:223], v188 offset:53248
	ds_read_b128 v[224:227], v188 offset:54272
	ds_read_b128 v[228:231], v188 offset:55296
	ds_read_b128 v[232:235], v188 offset:56320
	global_load_lds_dwordx4 v4, s[52:53] offset:128
	s_add_i32 m0, s4, 0x1f80
	s_add_u32 s22, s52, 0x160080
	s_addc_u32 s23, s53, 0
	s_add_i32 s4, s5, s24
	global_load_lds_dwordx4 v170, s[52:53] offset:128
	s_mov_b32 m0, s4
	s_nop 0
	global_load_lds_dwordx4 v4, s[22:23]
	s_add_i32 m0, s4, 0x2000
	s_nop 0
	global_load_lds_dwordx4 v170, s[22:23]
	s_add_i32 m0, s61, 0xffffff80
	s_nop 0
	global_load_lds_dwordx4 v2, s[54:55] offset:128
	s_add_i32 m0, s64, 0xffffff80
	s_nop 0
	global_load_lds_dwordx4 v168, s[54:55] offset:128
	s_waitcnt vmcnt(8)
	s_waitcnt lgkmcnt(0)
	s_barrier
	v_mfma_f32_16x16x32_bf16 v[58:61], v[134:137], v[184:187], v[58:61]
	v_mfma_f32_16x16x32_bf16 v[58:61], v[138:141], v[190:193], v[58:61]
	v_mfma_f32_16x16x32_bf16 v[54:57], v[142:145], v[184:187], v[54:57]
	v_mfma_f32_16x16x32_bf16 v[54:57], v[146:149], v[190:193], v[54:57]
	v_mfma_f32_16x16x32_bf16 v[66:69], v[150:153], v[184:187], v[66:69]
	v_mfma_f32_16x16x32_bf16 v[66:69], v[154:157], v[190:193], v[66:69]
	v_mfma_f32_16x16x32_bf16 v[62:65], v[176:179], v[184:187], v[62:65]
	v_mfma_f32_16x16x32_bf16 v[62:65], v[180:183], v[190:193], v[62:65]
	v_mfma_f32_16x16x32_bf16 v[38:41], v[176:179], v[212:215], v[38:41]
	v_mfma_f32_16x16x32_bf16 v[38:41], v[180:183], v[216:219], v[38:41]
	v_mfma_f32_16x16x32_bf16 v[42:45], v[150:153], v[212:215], v[42:45]
	v_mfma_f32_16x16x32_bf16 v[42:45], v[154:157], v[216:219], v[42:45]
	v_mfma_f32_16x16x32_bf16 v[46:49], v[142:145], v[212:215], v[46:49]
	v_mfma_f32_16x16x32_bf16 v[46:49], v[146:149], v[216:219], v[46:49]
	v_mfma_f32_16x16x32_bf16 v[50:53], v[134:137], v[212:215], v[50:53]
	v_mfma_f32_16x16x32_bf16 v[50:53], v[138:141], v[216:219], v[50:53]
	v_mfma_f32_16x16x32_bf16 v[34:37], v[134:137], v[220:223], v[34:37]
	v_mfma_f32_16x16x32_bf16 v[34:37], v[138:141], v[224:227], v[34:37]
	v_mfma_f32_16x16x32_bf16 v[30:33], v[142:145], v[220:223], v[30:33]
	v_mfma_f32_16x16x32_bf16 v[30:33], v[146:149], v[224:227], v[30:33]
	v_mfma_f32_16x16x32_bf16 v[26:29], v[150:153], v[220:223], v[26:29]
	v_mfma_f32_16x16x32_bf16 v[26:29], v[154:157], v[224:227], v[26:29]
	v_mfma_f32_16x16x32_bf16 v[22:25], v[176:179], v[220:223], v[22:25]
	v_mfma_f32_16x16x32_bf16 v[22:25], v[180:183], v[224:227], v[22:25]
	v_mfma_f32_16x16x32_bf16 v[6:9], v[176:179], v[228:231], v[6:9]
	v_mfma_f32_16x16x32_bf16 v[6:9], v[180:183], v[232:235], v[6:9]
	v_mfma_f32_16x16x32_bf16 v[10:13], v[150:153], v[228:231], v[10:13]
	v_mfma_f32_16x16x32_bf16 v[10:13], v[154:157], v[232:235], v[10:13]
	v_mfma_f32_16x16x32_bf16 v[14:17], v[142:145], v[228:231], v[14:17]
	v_mfma_f32_16x16x32_bf16 v[14:17], v[146:149], v[232:235], v[14:17]
	v_mfma_f32_16x16x32_bf16 v[18:21], v[134:137], v[228:231], v[18:21]
	v_mfma_f32_16x16x32_bf16 v[18:21], v[138:141], v[232:235], v[18:21]
	s_barrier
	s_add_i32 s20, s20, 2
	s_add_u32 s33, s33, 0x100
	s_addc_u32 s69, s69, 0
	s_cmpk_gt_u32 s20, 0x55
	s_mov_b64 s[22:23], s[50:51]
	s_cbranch_scc0 .LBB0_299
	s_and_b64 vcc, exec, s[46:47]
	s_cbranch_vccz .LBB0_302
	s_barrier

; #define PG8_STAGE(bufoff, gbase, voff) do { _Pragma("unroll") for (int _i = 0; _i < 2; ++_i) \
;         __builtin_amdgcn_global_load_lds((const unsigned*)((const char*)(gbase) + (voff)[_i]), (PG8_LAS unsigned*)(lds + (bufoff) + ldsw + _i * 8192), 16, 0, 0); } while (0)
; #define PG8_LDA(dst, b, h) do { _Pragma("unroll") for (int m = 0; m < 4; ++m) _Pragma("unroll") for (int k = 0; k < 2; ++k) dst[m][k] = *(const PG8_LAS bf16x8*)(lds + PG8_SA(b, h) + aoff + m * 2048 + k * 1024); } while (0)
; #define PG8_LDB(dst, b, h) do { _Pragma("unroll") for (int n = 0; n < 2; ++n) _Pragma("unroll") for (int k = 0; k < 2; ++k) dst[n][k] = *(const PG8_LAS bf16x8*)(lds + PG8_SB(b, h) + boff + n * 2048 + k * 1024); } while (0)
; #define PG8_MMA(ai, bj, At, Bt) do { __builtin_amdgcn_s_setprio(1); _Pragma("unroll") for (int m = 0; m < 4; ++m) _Pragma("unroll") for (int n = 0; n < 2; ++n) _Pragma("unroll") for (int k = 0; k < 2; ++k) \
;         acc[ai][bj][m][n] = __builtin_amdgcn_mfma_f32_16x16x32_bf16(Bt[n][k], At[m][k], acc[ai][bj][m][n], 0, 0, 0); __builtin_amdgcn_s_setprio(0); } while (0)
; #define PG8_WAIT_V(n) asm volatile("s_waitcnt vmcnt(" #n ")" ::: "memory")
; #define PG8_WAIT_L(n) asm volatile("s_waitcnt lgkmcnt(" #n ")" ::: "memory")
; #define PG8_BAR __builtin_amdgcn_s_barrier()
; #define PG8_SCHED __builtin_amdgcn_sched_barrier(0)
; template <class Epi, class Sched, bool ALIGN_EPI = false, bool SP2 = false>
; __device__ __forceinline__ void gemm_phase(PG8_LAS unsigned char* lds, const Gemm g, const Sched& S, const Epi& E) {
;     ...
;         for (int t = 0; t < nt; t += 2) {
;             const bool last = (t == nt - 2);
;             const char* a1 = cA + (size_t)(t + 1) * kstep;
;             const char* a2 = last ? nA : cA + (size_t)(t + 2) * kstep; const char* b2 = last ? nB : cB + (size_t)(t + 2) * kstep;
;             const char* a3 = a2 + kstep; const char* b3 = b2 + kstep;
;             if (last && has_next) S.a_ready(nxt);
;             if constexpr (SP2) {
;             PG8_LDB(B0, 0, 0); PG8_LDB(B1, 0, 1); PG8_SCHED; PG8_LDA(At, 0, 0); PG8_STAGE(PG8_SA(1, 1), a1 + hstep, voffA);
;             PG8_WAIT_V(8); PG8_WAIT_L(0); PG8_BAR; PG8_MMA(0, 0, At, B0); PG8_MMA(0, 1, At, B1); PG8_BAR; PG8_SCHED;
;             PG8_LDA(At, 0, 1); PG8_STAGE(PG8_SB(0, 0), b2, voffB); PG8_STAGE(PG8_SB(0, 1), b2 + hstep, voffB); PG8_STAGE(PG8_SA(0, 0), a2, voffA);
.LBB0_386:
	s_ashr_i32 s47, s46, 31
	s_lshl_b64 s[34:35], s[46:47], 20
	s_add_u32 s50, s96, s34
	s_addc_u32 s51, s97, s35
	s_and_b64 s[34:35], s[36:37], exec
	s_cselect_b32 s47, s51, s57
	s_cselect_b32 s75, s50, s56
	s_ashr_i32 s49, s48, 31
	s_lshl_b64 s[34:35], s[48:49], 20
	s_add_u32 s52, s2, s34
	s_addc_u32 s53, s3, s35
	s_and_b64 s[34:35], s[36:37], exec
	s_cselect_b32 s49, s53, s55
	s_cselect_b32 vcc_lo, s52, s54
	s_add_u32 s56, s56, 0x80080
	s_addc_u32 s57, s57, 0
	s_add_u32 s71, s54, 0x100
	s_addc_u32 s77, s55, 0
	s_mov_b32 s20, -2
	v_add_u32_e32 v156, 0x10000, v153
	v_add_u32_e32 v157, 0x14000, v153
	v_add_u32_e32 v192, 0x18000, v153
	v_add_u32_e32 v193, 0x1c000, v153
.LBB0_387:
	ds_read_b128 v[144:147], v156
	ds_read_b128 v[148:151], v156 offset:1024
	ds_read_b128 v[168:171], v156 offset:2048
	ds_read_b128 v[172:175], v156 offset:3072
	ds_read_b128 v[176:179], v157
	ds_read_b128 v[180:183], v157 offset:1024
	ds_read_b128 v[184:187], v157 offset:2048
	ds_read_b128 v[188:191], v157 offset:3072
	ds_read_b128 v[212:215], v155
	ds_read_b128 v[216:219], v155 offset:1024
	ds_read_b128 v[220:223], v155 offset:2048
	ds_read_b128 v[224:227], v155 offset:3072
	ds_read_b128 v[228:231], v155 offset:4096
	ds_read_b128 v[232:235], v155 offset:5120
	ds_read_b128 v[236:239], v155 offset:6144
	ds_read_b128 v[240:243], v155 offset:7168
	s_add_i32 m0, s60, 0xc000
	s_add_u32 s4, s56, 0xfff80080
	s_addc_u32 s5, s57, -1
	global_load_lds_dwordx4 v140, s[56:57]
	s_add_i32 m0, s60, 0xe000
	s_add_i32 s6, 0, 0x10000
	global_load_lds_dwordx4 v142, s[56:57]
	s_cmp_eq_u32 s20, 28
	s_cselect_b32 s59, s47, s5
	s_cselect_b32 s58, s75, s4
	s_cselect_b32 s55, s49, s77
	s_cselect_b32 s54, vcc_lo, s71
	s_add_i32 s4, 0, 0x14000
	s_waitcnt vmcnt(8)
	s_waitcnt lgkmcnt(0)
	s_barrier
	v_mfma_f32_16x16x32_bf16 v[122:125], v[144:147], v[212:215], v[122:125]
	v_mfma_f32_16x16x32_bf16 v[122:125], v[148:151], v[216:219], v[122:125]
	v_mfma_f32_16x16x32_bf16 v[118:121], v[168:171], v[212:215], v[118:121]
	v_mfma_f32_16x16x32_bf16 v[118:121], v[172:175], v[216:219], v[118:121]
	v_mfma_f32_16x16x32_bf16 v[130:133], v[176:179], v[212:215], v[130:133]
	v_mfma_f32_16x16x32_bf16 v[130:133], v[180:183], v[216:219], v[130:133]
	v_mfma_f32_16x16x32_bf16 v[126:129], v[184:187], v[212:215], v[126:129]
	v_mfma_f32_16x16x32_bf16 v[126:129], v[188:191], v[216:219], v[126:129]
	v_mfma_f32_16x16x32_bf16 v[110:113], v[184:187], v[220:223], v[110:113]
	v_mfma_f32_16x16x32_bf16 v[110:113], v[188:191], v[224:227], v[110:113]
	v_mfma_f32_16x16x32_bf16 v[114:117], v[176:179], v[220:223], v[114:117]
	v_mfma_f32_16x16x32_bf16 v[114:117], v[180:183], v[224:227], v[114:117]
	v_mfma_f32_16x16x32_bf16 v[102:105], v[168:171], v[220:223], v[102:105]
	v_mfma_f32_16x16x32_bf16 v[102:105], v[172:175], v[224:227], v[102:105]
	v_mfma_f32_16x16x32_bf16 v[106:109], v[144:147], v[220:223], v[106:109]
	v_mfma_f32_16x16x32_bf16 v[106:109], v[148:151], v[224:227], v[106:109]
	v_mfma_f32_16x16x32_bf16 v[90:93], v[144:147], v[228:231], v[90:93]
	v_mfma_f32_16x16x32_bf16 v[90:93], v[148:151], v[232:235], v[90:93]
	v_mfma_f32_16x16x32_bf16 v[86:89], v[168:171], v[228:231], v[86:89]
	v_mfma_f32_16x16x32_bf16 v[86:89], v[172:175], v[232:235], v[86:89]
	v_mfma_f32_16x16x32_bf16 v[98:101], v[176:179], v[228:231], v[98:101]
	v_mfma_f32_16x16x32_bf16 v[98:101], v[180:183], v[232:235], v[98:101]
	v_mfma_f32_16x16x32_bf16 v[94:97], v[184:187], v[228:231], v[94:97]
	v_mfma_f32_16x16x32_bf16 v[94:97], v[188:191], v[232:235], v[94:97]
	v_mfma_f32_16x16x32_bf16 v[78:81], v[184:187], v[236:239], v[78:81]
	v_mfma_f32_16x16x32_bf16 v[78:81], v[188:191], v[240:243], v[78:81]
	v_mfma_f32_16x16x32_bf16 v[82:85], v[176:179], v[236:239], v[82:85]
	v_mfma_f32_16x16x32_bf16 v[82:85], v[180:183], v[240:243], v[82:85]
	v_mfma_f32_16x16x32_bf16 v[70:73], v[168:171], v[236:239], v[70:73]
	v_mfma_f32_16x16x32_bf16 v[70:73], v[172:175], v[240:243], v[70:73]
	v_mfma_f32_16x16x32_bf16 v[74:77], v[144:147], v[236:239], v[74:77]
	v_mfma_f32_16x16x32_bf16 v[74:77], v[148:151], v[240:243], v[74:77]
	s_barrier
	ds_read_b128 v[212:215], v155 offset:16384
	ds_read_b128 v[216:219], v155 offset:17408
	ds_read_b128 v[220:223], v155 offset:18432
	ds_read_b128 v[224:227], v155 offset:19456
	ds_read_b128 v[228:231], v155 offset:20480
	ds_read_b128 v[232:235], v155 offset:21504
	ds_read_b128 v[236:239], v155 offset:22528
	ds_read_b128 v[240:243], v155 offset:23552
	s_add_i32 s5, s6, s24
	s_mov_b32 m0, s5
	s_add_u32 s34, s54, 0x80000
	s_addc_u32 s35, s55, 0
	global_load_lds_dwordx4 v4, s[54:55]
	s_add_i32 m0, s5, 0x2000
	s_add_i32 s4, s4, s24
	global_load_lds_dwordx4 v2, s[54:55]
	s_mov_b32 m0, s4
	s_nop 0
	global_load_lds_dwordx4 v4, s[34:35]
	s_add_i32 m0, s4, 0x2000
	s_nop 0
	global_load_lds_dwordx4 v2, s[34:35]
	s_mov_b32 m0, s60
	s_nop 0
	global_load_lds_dwordx4 v136, s[58:59]
	s_mov_b32 m0, s61
	s_nop 0
	global_load_lds_dwordx4 v134, s[58:59]
	s_waitcnt vmcnt(8)
	s_waitcnt lgkmcnt(0)
	s_barrier
; #define PG8_STAGE(bufoff, gbase, voff) do { _Pragma("unroll") for (int _i = 0; _i < 2; ++_i) \
;         __builtin_amdgcn_global_load_lds((const unsigned*)((const char*)(gbase) + (voff)[_i]), (PG8_LAS unsigned*)(lds + (bufoff) + ldsw + _i * 8192), 16, 0, 0); } while (0)
; #define PG8_LDA(dst, b, h) do { _Pragma("unroll") for (int m = 0; m < 4; ++m) _Pragma("unroll") for (int k = 0; k < 2; ++k) dst[m][k] = *(const PG8_LAS bf16x8*)(lds + PG8_SA(b, h) + aoff + m * 2048 + k * 1024); } while (0)
; #define PG8_LDB(dst, b, h) do { _Pragma("unroll") for (int n = 0; n < 2; ++n) _Pragma("unroll") for (int k = 0; k < 2; ++k) dst[n][k] = *(const PG8_LAS bf16x8*)(lds + PG8_SB(b, h) + boff + n * 2048 + k * 1024); } while (0)
; #define PG8_MMA(ai, bj, At, Bt) do { __builtin_amdgcn_s_setprio(1); _Pragma("unroll") for (int m = 0; m < 4; ++m) _Pragma("unroll") for (int n = 0; n < 2; ++n) _Pragma("unroll") for (int k = 0; k < 2; ++k) \
;         acc[ai][bj][m][n] = __builtin_amdgcn_mfma_f32_16x16x32_bf16(Bt[n][k], At[m][k], acc[ai][bj][m][n], 0, 0, 0); __builtin_amdgcn_s_setprio(0); } while (0)
; #define PG8_WAIT_V(n) asm volatile("s_waitcnt vmcnt(" #n ")" ::: "memory")
; #define PG8_WAIT_L(n) asm volatile("s_waitcnt lgkmcnt(" #n ")" ::: "memory")
; #define PG8_BAR __builtin_amdgcn_s_barrier()
; #define PG8_SCHED __builtin_amdgcn_sched_barrier(0)
; template <class Epi, class Sched, bool ALIGN_EPI = false, bool SP2 = false>
; __device__ __forceinline__ void gemm_phase(PG8_LAS unsigned char* lds, const Gemm g, const Sched& S, const Epi& E) {
;     ...
;             PG8_WAIT_V(8); PG8_WAIT_L(0); PG8_BAR; PG8_MMA(1, 0, At, B0); PG8_MMA(1, 1, At, B1); PG8_BAR; PG8_SCHED;
;             PG8_LDB(B0, 1, 0); PG8_LDB(B1, 1, 1); PG8_SCHED; PG8_LDA(At, 1, 0); PG8_STAGE(PG8_SA(0, 1), a2 + hstep, voffA);
;             PG8_WAIT_V(8); PG8_WAIT_L(0); PG8_BAR; PG8_MMA(0, 0, At, B0); PG8_MMA(0, 1, At, B1); PG8_BAR; PG8_SCHED;
	v_mfma_f32_16x16x32_bf16 v[58:61], v[144:147], v[212:215], v[58:61]
	v_mfma_f32_16x16x32_bf16 v[58:61], v[148:151], v[216:219], v[58:61]
	v_mfma_f32_16x16x32_bf16 v[54:57], v[168:171], v[212:215], v[54:57]
	v_mfma_f32_16x16x32_bf16 v[54:57], v[172:175], v[216:219], v[54:57]
	v_mfma_f32_16x16x32_bf16 v[66:69], v[176:179], v[212:215], v[66:69]
	v_mfma_f32_16x16x32_bf16 v[66:69], v[180:183], v[216:219], v[66:69]
	v_mfma_f32_16x16x32_bf16 v[62:65], v[184:187], v[212:215], v[62:65]
	v_mfma_f32_16x16x32_bf16 v[62:65], v[188:191], v[216:219], v[62:65]
	v_mfma_f32_16x16x32_bf16 v[46:49], v[184:187], v[220:223], v[46:49]
	v_mfma_f32_16x16x32_bf16 v[46:49], v[188:191], v[224:227], v[46:49]
	v_mfma_f32_16x16x32_bf16 v[50:53], v[176:179], v[220:223], v[50:53]
	v_mfma_f32_16x16x32_bf16 v[50:53], v[180:183], v[224:227], v[50:53]
	v_mfma_f32_16x16x32_bf16 v[38:41], v[168:171], v[220:223], v[38:41]
	v_mfma_f32_16x16x32_bf16 v[38:41], v[172:175], v[224:227], v[38:41]
	v_mfma_f32_16x16x32_bf16 v[42:45], v[144:147], v[220:223], v[42:45]
	v_mfma_f32_16x16x32_bf16 v[42:45], v[148:151], v[224:227], v[42:45]
	v_mfma_f32_16x16x32_bf16 v[26:29], v[144:147], v[228:231], v[26:29]
	v_mfma_f32_16x16x32_bf16 v[26:29], v[148:151], v[232:235], v[26:29]
	v_mfma_f32_16x16x32_bf16 v[22:25], v[168:171], v[228:231], v[22:25]
	v_mfma_f32_16x16x32_bf16 v[22:25], v[172:175], v[232:235], v[22:25]
	v_mfma_f32_16x16x32_bf16 v[34:37], v[176:179], v[228:231], v[34:37]
	v_mfma_f32_16x16x32_bf16 v[34:37], v[180:183], v[232:235], v[34:37]
	v_mfma_f32_16x16x32_bf16 v[30:33], v[184:187], v[228:231], v[30:33]
	v_mfma_f32_16x16x32_bf16 v[30:33], v[188:191], v[232:235], v[30:33]
	v_mfma_f32_16x16x32_bf16 v[18:21], v[184:187], v[236:239], v[18:21]
	v_mfma_f32_16x16x32_bf16 v[18:21], v[188:191], v[240:243], v[18:21]
	v_mfma_f32_16x16x32_bf16 v[14:17], v[176:179], v[236:239], v[14:17]
	v_mfma_f32_16x16x32_bf16 v[14:17], v[180:183], v[240:243], v[14:17]
	v_mfma_f32_16x16x32_bf16 v[6:9], v[168:171], v[236:239], v[6:9]
	v_mfma_f32_16x16x32_bf16 v[6:9], v[172:175], v[240:243], v[6:9]
	v_mfma_f32_16x16x32_bf16 v[10:13], v[144:147], v[236:239], v[10:13]
	v_mfma_f32_16x16x32_bf16 v[10:13], v[148:151], v[240:243], v[10:13]
	s_barrier
	ds_read_b128 v[144:147], v192
	ds_read_b128 v[148:151], v192 offset:1024
	ds_read_b128 v[168:171], v192 offset:2048
	ds_read_b128 v[172:175], v192 offset:3072
	ds_read_b128 v[176:179], v193
	ds_read_b128 v[180:183], v193 offset:1024
	ds_read_b128 v[184:187], v193 offset:2048
	ds_read_b128 v[188:191], v193 offset:3072
	ds_read_b128 v[212:215], v155 offset:32768
	ds_read_b128 v[216:219], v155 offset:33792
	ds_read_b128 v[220:223], v155 offset:34816
	ds_read_b128 v[224:227], v155 offset:35840
	ds_read_b128 v[228:231], v155 offset:36864
	ds_read_b128 v[232:235], v155 offset:37888
	ds_read_b128 v[236:239], v155 offset:38912
	ds_read_b128 v[240:243], v155 offset:39936
	s_add_u32 s34, s58, 0x80000
	s_addc_u32 s35, s59, 0
	s_mov_b32 m0, s64
	s_add_i32 s4, 0, 0x18000
	global_load_lds_dwordx4 v136, s[34:35]
	s_mov_b32 m0, s65
	s_add_i32 s5, 0, 0x1c000
	global_load_lds_dwordx4 v134, s[34:35]
	s_waitcnt vmcnt(8)
	s_waitcnt lgkmcnt(0)
	s_barrier
	v_mfma_f32_16x16x32_bf16 v[122:125], v[144:147], v[212:215], v[122:125]
	v_mfma_f32_16x16x32_bf16 v[122:125], v[148:151], v[216:219], v[122:125]
	v_mfma_f32_16x16x32_bf16 v[118:121], v[168:171], v[212:215], v[118:121]
	v_mfma_f32_16x16x32_bf16 v[118:121], v[172:175], v[216:219], v[118:121]
	v_mfma_f32_16x16x32_bf16 v[130:133], v[176:179], v[212:215], v[130:133]
	v_mfma_f32_16x16x32_bf16 v[130:133], v[180:183], v[216:219], v[130:133]
	v_mfma_f32_16x16x32_bf16 v[126:129], v[184:187], v[212:215], v[126:129]
	v_mfma_f32_16x16x32_bf16 v[126:129], v[188:191], v[216:219], v[126:129]
	v_mfma_f32_16x16x32_bf16 v[110:113], v[184:187], v[220:223], v[110:113]
	v_mfma_f32_16x16x32_bf16 v[110:113], v[188:191], v[224:227], v[110:113]
	v_mfma_f32_16x16x32_bf16 v[114:117], v[176:179], v[220:223], v[114:117]
	v_mfma_f32_16x16x32_bf16 v[114:117], v[180:183], v[224:227], v[114:117]
	v_mfma_f32_16x16x32_bf16 v[102:105], v[168:171], v[220:223], v[102:105]
	v_mfma_f32_16x16x32_bf16 v[102:105], v[172:175], v[224:227], v[102:105]
	v_mfma_f32_16x16x32_bf16 v[106:109], v[144:147], v[220:223], v[106:109]
	v_mfma_f32_16x16x32_bf16 v[106:109], v[148:151], v[224:227], v[106:109]
	v_mfma_f32_16x16x32_bf16 v[90:93], v[144:147], v[228:231], v[90:93]
	v_mfma_f32_16x16x32_bf16 v[90:93], v[148:151], v[232:235], v[90:93]
	v_mfma_f32_16x16x32_bf16 v[86:89], v[168:171], v[228:231], v[86:89]
	v_mfma_f32_16x16x32_bf16 v[86:89], v[172:175], v[232:235], v[86:89]
	v_mfma_f32_16x16x32_bf16 v[98:101], v[176:179], v[228:231], v[98:101]
	v_mfma_f32_16x16x32_bf16 v[98:101], v[180:183], v[232:235], v[98:101]
	v_mfma_f32_16x16x32_bf16 v[94:97], v[184:187], v[228:231], v[94:97]
	v_mfma_f32_16x16x32_bf16 v[94:97], v[188:191], v[232:235], v[94:97]
	v_mfma_f32_16x16x32_bf16 v[78:81], v[184:187], v[236:239], v[78:81]
	v_mfma_f32_16x16x32_bf16 v[78:81], v[188:191], v[240:243], v[78:81]
	v_mfma_f32_16x16x32_bf16 v[82:85], v[176:179], v[236:239], v[82:85]
	v_mfma_f32_16x16x32_bf16 v[82:85], v[180:183], v[240:243], v[82:85]
	v_mfma_f32_16x16x32_bf16 v[70:73], v[168:171], v[236:239], v[70:73]
	v_mfma_f32_16x16x32_bf16 v[70:73], v[172:175], v[240:243], v[70:73]
	v_mfma_f32_16x16x32_bf16 v[74:77], v[144:147], v[236:239], v[74:77]
	v_mfma_f32_16x16x32_bf16 v[74:77], v[148:151], v[240:243], v[74:77]
	s_barrier
; #define PG8_STAGE(bufoff, gbase, voff) do { _Pragma("unroll") for (int _i = 0; _i < 2; ++_i) \
;         __builtin_amdgcn_global_load_lds((const unsigned*)((const char*)(gbase) + (voff)[_i]), (PG8_LAS unsigned*)(lds + (bufoff) + ldsw + _i * 8192), 16, 0, 0); } while (0)
; #define PG8_LDA(dst, b, h) do { _Pragma("unroll") for (int m = 0; m < 4; ++m) _Pragma("unroll") for (int k = 0; k < 2; ++k) dst[m][k] = *(const PG8_LAS bf16x8*)(lds + PG8_SA(b, h) + aoff + m * 2048 + k * 1024); } while (0)
; #define PG8_MMA(ai, bj, At, Bt) do { __builtin_amdgcn_s_setprio(1); _Pragma("unroll") for (int m = 0; m < 4; ++m) _Pragma("unroll") for (int n = 0; n < 2; ++n) _Pragma("unroll") for (int k = 0; k < 2; ++k) \
;         acc[ai][bj][m][n] = __builtin_amdgcn_mfma_f32_16x16x32_bf16(Bt[n][k], At[m][k], acc[ai][bj][m][n], 0, 0, 0); __builtin_amdgcn_s_setprio(0); } while (0)
; #define PG8_WAIT_V(n) asm volatile("s_waitcnt vmcnt(" #n ")" ::: "memory")
; #define PG8_WAIT_L(n) asm volatile("s_waitcnt lgkmcnt(" #n ")" ::: "memory")
; #define PG8_BAR __builtin_amdgcn_s_barrier()
; #define PG8_SCHED __builtin_amdgcn_sched_barrier(0)
; template <class Epi, class Sched, bool ALIGN_EPI = false, bool SP2 = false>
; __device__ __forceinline__ void gemm_phase(PG8_LAS unsigned char* lds, const Gemm g, const Sched& S, const Epi& E) {
;     ...
;         for (int t = 0; t < nt; t += 2) {
;     ...
;             PG8_LDA(At, 1, 1); PG8_STAGE(PG8_SB(1, 0), b3, voffB); PG8_STAGE(PG8_SB(1, 1), b3 + hstep, voffB); PG8_STAGE(PG8_SA(1, 0), a3, voffA);
;             PG8_WAIT_V(8); PG8_WAIT_L(0); PG8_BAR; PG8_MMA(1, 0, At, B0); PG8_MMA(1, 1, At, B1); PG8_BAR; PG8_SCHED;
	ds_read_b128 v[212:215], v155 offset:49152
	ds_read_b128 v[216:219], v155 offset:50176
	ds_read_b128 v[220:223], v155 offset:51200
	ds_read_b128 v[224:227], v155 offset:52224
	ds_read_b128 v[228:231], v155 offset:53248
	ds_read_b128 v[232:235], v155 offset:54272
	ds_read_b128 v[236:239], v155 offset:55296
	ds_read_b128 v[240:243], v155 offset:56320
	s_add_i32 s4, s4, s24
	s_add_i32 m0, s4, 0xffffff80
	s_nop 0
	global_load_lds_dwordx4 v4, s[54:55] offset:128
	s_add_i32 m0, s4, 0x1f80
	s_add_i32 s4, s5, s24
	global_load_lds_dwordx4 v2, s[54:55] offset:128
	s_add_u32 s34, s54, 0x80080
	s_addc_u32 s35, s55, 0
	s_mov_b32 m0, s4
	s_nop 0
	global_load_lds_dwordx4 v4, s[34:35]
	s_add_i32 m0, s4, 0x2000
	s_nop 0
	global_load_lds_dwordx4 v2, s[34:35]
	s_add_i32 m0, s67, 0xffffff80
	s_nop 0
	global_load_lds_dwordx4 v136, s[58:59] offset:128
	s_add_i32 m0, s72, 0xffffff80
	s_nop 0
	global_load_lds_dwordx4 v134, s[58:59] offset:128
	s_waitcnt vmcnt(8)
	s_waitcnt lgkmcnt(0)
	s_barrier
	v_mfma_f32_16x16x32_bf16 v[58:61], v[144:147], v[212:215], v[58:61]
	v_mfma_f32_16x16x32_bf16 v[58:61], v[148:151], v[216:219], v[58:61]
	v_mfma_f32_16x16x32_bf16 v[54:57], v[168:171], v[212:215], v[54:57]
	v_mfma_f32_16x16x32_bf16 v[54:57], v[172:175], v[216:219], v[54:57]
	v_mfma_f32_16x16x32_bf16 v[66:69], v[176:179], v[212:215], v[66:69]
	v_mfma_f32_16x16x32_bf16 v[66:69], v[180:183], v[216:219], v[66:69]
	v_mfma_f32_16x16x32_bf16 v[62:65], v[184:187], v[212:215], v[62:65]
	v_mfma_f32_16x16x32_bf16 v[62:65], v[188:191], v[216:219], v[62:65]
	v_mfma_f32_16x16x32_bf16 v[46:49], v[184:187], v[220:223], v[46:49]
	v_mfma_f32_16x16x32_bf16 v[46:49], v[188:191], v[224:227], v[46:49]
	v_mfma_f32_16x16x32_bf16 v[50:53], v[176:179], v[220:223], v[50:53]
	v_mfma_f32_16x16x32_bf16 v[50:53], v[180:183], v[224:227], v[50:53]
	v_mfma_f32_16x16x32_bf16 v[38:41], v[168:171], v[220:223], v[38:41]
	v_mfma_f32_16x16x32_bf16 v[38:41], v[172:175], v[224:227], v[38:41]
	v_mfma_f32_16x16x32_bf16 v[42:45], v[144:147], v[220:223], v[42:45]
	v_mfma_f32_16x16x32_bf16 v[42:45], v[148:151], v[224:227], v[42:45]
	v_mfma_f32_16x16x32_bf16 v[26:29], v[144:147], v[228:231], v[26:29]
	v_mfma_f32_16x16x32_bf16 v[26:29], v[148:151], v[232:235], v[26:29]
	v_mfma_f32_16x16x32_bf16 v[22:25], v[168:171], v[228:231], v[22:25]
	v_mfma_f32_16x16x32_bf16 v[22:25], v[172:175], v[232:235], v[22:25]
	v_mfma_f32_16x16x32_bf16 v[34:37], v[176:179], v[228:231], v[34:37]
	v_mfma_f32_16x16x32_bf16 v[34:37], v[180:183], v[232:235], v[34:37]
	v_mfma_f32_16x16x32_bf16 v[30:33], v[184:187], v[228:231], v[30:33]
	v_mfma_f32_16x16x32_bf16 v[30:33], v[188:191], v[232:235], v[30:33]
	v_mfma_f32_16x16x32_bf16 v[18:21], v[184:187], v[236:239], v[18:21]
	v_mfma_f32_16x16x32_bf16 v[18:21], v[188:191], v[240:243], v[18:21]
	v_mfma_f32_16x16x32_bf16 v[14:17], v[176:179], v[236:239], v[14:17]
	v_mfma_f32_16x16x32_bf16 v[14:17], v[180:183], v[240:243], v[14:17]
	v_mfma_f32_16x16x32_bf16 v[6:9], v[168:171], v[236:239], v[6:9]
	v_mfma_f32_16x16x32_bf16 v[6:9], v[172:175], v[240:243], v[6:9]
	v_mfma_f32_16x16x32_bf16 v[10:13], v[144:147], v[236:239], v[10:13]
	v_mfma_f32_16x16x32_bf16 v[10:13], v[148:151], v[240:243], v[10:13]
	s_barrier
	s_add_i32 s20, s20, 2
	s_add_u32 s56, s56, 0x100
	s_addc_u32 s57, s57, 0
	s_add_u32 s71, s71, 0x100
	s_addc_u32 s77, s77, 0
	s_cmp_gt_u32 s20, 29
	s_cbranch_scc0 .LBB0_387
	s_and_b64 vcc, exec, s[44:45]
	s_movk_i32 s75, 0x800
	s_movk_i32 s77, 0x6000
	s_mov_b32 s71, 0x44800000
	s_cbranch_vccz .LBB0_390
	s_barrier

; #define PG8_STAGE(bufoff, gbase, voff) do { _Pragma("unroll") for (int _i = 0; _i < 2; ++_i) \
;         __builtin_amdgcn_global_load_lds((const unsigned*)((const char*)(gbase) + (voff)[_i]), (PG8_LAS unsigned*)(lds + (bufoff) + ldsw + _i * 8192), 16, 0, 0); } while (0)
; #define PG8_LDA(dst, b, h) do { _Pragma("unroll") for (int m = 0; m < 4; ++m) _Pragma("unroll") for (int k = 0; k < 2; ++k) dst[m][k] = *(const PG8_LAS bf16x8*)(lds + PG8_SA(b, h) + aoff + m * 2048 + k * 1024); } while (0)
; #define PG8_LDB(dst, b, h) do { _Pragma("unroll") for (int n = 0; n < 2; ++n) _Pragma("unroll") for (int k = 0; k < 2; ++k) dst[n][k] = *(const PG8_LAS bf16x8*)(lds + PG8_SB(b, h) + boff + n * 2048 + k * 1024); } while (0)
; #define PG8_MMA(ai, bj, At, Bt) do { __builtin_amdgcn_s_setprio(1); _Pragma("unroll") for (int m = 0; m < 4; ++m) _Pragma("unroll") for (int n = 0; n < 2; ++n) _Pragma("unroll") for (int k = 0; k < 2; ++k) \
;         acc[ai][bj][m][n] = __builtin_amdgcn_mfma_f32_16x16x32_bf16(Bt[n][k], At[m][k], acc[ai][bj][m][n], 0, 0, 0); __builtin_amdgcn_s_setprio(0); } while (0)
; #define PG8_WAIT_V(n) asm volatile("s_waitcnt vmcnt(" #n ")" ::: "memory")
; #define PG8_WAIT_L(n) asm volatile("s_waitcnt lgkmcnt(" #n ")" ::: "memory")
; #define PG8_BAR __builtin_amdgcn_s_barrier()
; #define PG8_SCHED __builtin_amdgcn_sched_barrier(0)
; template <class Epi, class Sched, bool ALIGN_EPI = false, bool SP2 = false>
; __device__ __forceinline__ void gemm_phase(PG8_LAS unsigned char* lds, const Gemm g, const Sched& S, const Epi& E) {
;     ...
;         for (int t = 0; t < nt; t += 2) {
;             const bool last = (t == nt - 2);
;             const char* a1 = cA + (size_t)(t + 1) * kstep;
;             const char* a2 = last ? nA : cA + (size_t)(t + 2) * kstep; const char* b2 = last ? nB : cB + (size_t)(t + 2) * kstep;
;             const char* a3 = a2 + kstep; const char* b3 = b2 + kstep;
;             if (last && has_next) S.a_ready(nxt);
;             if constexpr (SP2) {
;             PG8_LDB(B0, 0, 0); PG8_LDB(B1, 0, 1); PG8_SCHED; PG8_LDA(At, 0, 0); PG8_STAGE(PG8_SA(1, 1), a1 + hstep, voffA);
;             PG8_WAIT_V(8); PG8_WAIT_L(0); PG8_BAR; PG8_MMA(0, 0, At, B0); PG8_MMA(0, 1, At, B1); PG8_BAR; PG8_SCHED;
;             PG8_LDA(At, 0, 1); PG8_STAGE(PG8_SB(0, 0), b2, voffB); PG8_STAGE(PG8_SB(0, 1), b2 + hstep, voffB); PG8_STAGE(PG8_SA(0, 0), a2, voffA);
.LBB0_1737:
	s_ashr_i32 s43, s42, 31
	s_lshl_b64 s[22:23], s[42:43], 20
	s_add_u32 s22, s58, s22
	s_addc_u32 s23, s59, s23
	s_and_b64 s[34:35], s[38:39], exec
	s_cselect_b32 s43, s23, s51
	s_cselect_b32 s66, s22, s50
	s_ashr_i32 s45, s44, 31
	s_lshl_b64 s[34:35], s[44:45], 20
	s_add_u32 s46, s2, s34
	s_addc_u32 s47, s3, s35
	s_and_b64 s[34:35], s[38:39], exec
	s_cselect_b32 s45, s47, s49
	s_cselect_b32 s67, s46, s48
	s_add_u32 s50, s50, 0x80080
	s_addc_u32 s51, s51, 0
	s_add_u32 s69, s48, 0x100
	s_addc_u32 s71, s49, 0
	s_mov_b32 s20, -2
	v_add_u32_e32 v234, 0x10000, v158
	v_add_u32_e32 v235, 0x14000, v158
	v_add_u32_e32 v236, 0x18000, v158
	v_add_u32_e32 v237, 0x1c000, v158
.LBB0_1738:
	s_add_u32 s4, s50, 0xfff80080
	s_addc_u32 s5, s51, -1
	s_add_i32 s6, 0, 0x10000
	s_cmp_eq_u32 s20, 28
	s_cselect_b32 s53, s43, s5
	s_cselect_b32 s52, s66, s4
	s_cselect_b32 s49, s45, s71
	s_cselect_b32 s48, s67, s69
	s_add_i32 s4, 0, 0x14000
	ds_read_b128 v[134:137], v234
	ds_read_b128 v[138:141], v234 offset:1024
	ds_read_b128 v[142:145], v234 offset:2048
	ds_read_b128 v[146:149], v234 offset:3072
	ds_read_b128 v[150:153], v235
	ds_read_b128 v[154:157], v235 offset:1024
	ds_read_b128 v[176:179], v235 offset:2048
	ds_read_b128 v[180:183], v235 offset:3072
	s_add_i32 m0, s54, 0xc000
	ds_read_b128 v[184:187], v188
	ds_read_b128 v[190:193], v188 offset:1024
	ds_read_b128 v[210:213], v188 offset:2048
	ds_read_b128 v[214:217], v188 offset:3072
	ds_read_b128 v[218:221], v188 offset:4096
	ds_read_b128 v[222:225], v188 offset:5120
	ds_read_b128 v[226:229], v188 offset:6144
	ds_read_b128 v[230:233], v188 offset:7168
	global_load_lds_dwordx4 v172, s[50:51]
	s_add_i32 m0, s54, 0xe000
	s_nop 0
	global_load_lds_dwordx4 v174, s[50:51]
	s_waitcnt vmcnt(8)
	s_waitcnt lgkmcnt(0)
	s_barrier
	v_mfma_f32_16x16x32_bf16 v[122:125], v[134:137], v[184:187], v[122:125]
	v_mfma_f32_16x16x32_bf16 v[122:125], v[138:141], v[190:193], v[122:125]
	v_mfma_f32_16x16x32_bf16 v[118:121], v[142:145], v[184:187], v[118:121]
	v_mfma_f32_16x16x32_bf16 v[118:121], v[146:149], v[190:193], v[118:121]
	v_mfma_f32_16x16x32_bf16 v[130:133], v[150:153], v[184:187], v[130:133]
	v_mfma_f32_16x16x32_bf16 v[130:133], v[154:157], v[190:193], v[130:133]
	v_mfma_f32_16x16x32_bf16 v[126:129], v[176:179], v[184:187], v[126:129]
	v_mfma_f32_16x16x32_bf16 v[126:129], v[180:183], v[190:193], v[126:129]
	v_mfma_f32_16x16x32_bf16 v[102:105], v[176:179], v[210:213], v[102:105]
	v_mfma_f32_16x16x32_bf16 v[102:105], v[180:183], v[214:217], v[102:105]
	v_mfma_f32_16x16x32_bf16 v[110:113], v[150:153], v[210:213], v[110:113]
	v_mfma_f32_16x16x32_bf16 v[110:113], v[154:157], v[214:217], v[110:113]
	v_mfma_f32_16x16x32_bf16 v[106:109], v[142:145], v[210:213], v[106:109]
	v_mfma_f32_16x16x32_bf16 v[106:109], v[146:149], v[214:217], v[106:109]
	v_mfma_f32_16x16x32_bf16 v[114:117], v[134:137], v[210:213], v[114:117]
	v_mfma_f32_16x16x32_bf16 v[114:117], v[138:141], v[214:217], v[114:117]
	v_mfma_f32_16x16x32_bf16 v[98:101], v[134:137], v[218:221], v[98:101]
	v_mfma_f32_16x16x32_bf16 v[98:101], v[138:141], v[222:225], v[98:101]
	v_mfma_f32_16x16x32_bf16 v[90:93], v[142:145], v[218:221], v[90:93]
	v_mfma_f32_16x16x32_bf16 v[90:93], v[146:149], v[222:225], v[90:93]
	v_mfma_f32_16x16x32_bf16 v[94:97], v[150:153], v[218:221], v[94:97]
	v_mfma_f32_16x16x32_bf16 v[94:97], v[154:157], v[222:225], v[94:97]
	v_mfma_f32_16x16x32_bf16 v[86:89], v[176:179], v[218:221], v[86:89]
	v_mfma_f32_16x16x32_bf16 v[86:89], v[180:183], v[222:225], v[86:89]
	v_mfma_f32_16x16x32_bf16 v[70:73], v[176:179], v[226:229], v[70:73]
	v_mfma_f32_16x16x32_bf16 v[70:73], v[180:183], v[230:233], v[70:73]
	v_mfma_f32_16x16x32_bf16 v[78:81], v[150:153], v[226:229], v[78:81]
	v_mfma_f32_16x16x32_bf16 v[78:81], v[154:157], v[230:233], v[78:81]
	v_mfma_f32_16x16x32_bf16 v[74:77], v[142:145], v[226:229], v[74:77]
	v_mfma_f32_16x16x32_bf16 v[74:77], v[146:149], v[230:233], v[74:77]
	v_mfma_f32_16x16x32_bf16 v[82:85], v[134:137], v[226:229], v[82:85]
	v_mfma_f32_16x16x32_bf16 v[82:85], v[138:141], v[230:233], v[82:85]
	s_barrier
	s_add_i32 s5, s6, s24
	s_mov_b32 m0, s5
	ds_read_b128 v[184:187], v188 offset:16384
	ds_read_b128 v[190:193], v188 offset:17408
	ds_read_b128 v[210:213], v188 offset:18432
	ds_read_b128 v[214:217], v188 offset:19456
	ds_read_b128 v[218:221], v188 offset:20480
	ds_read_b128 v[222:225], v188 offset:21504
	ds_read_b128 v[226:229], v188 offset:22528
	ds_read_b128 v[230:233], v188 offset:23552
	global_load_lds_dwordx4 v4, s[48:49]
	s_add_i32 m0, s5, 0x2000
	s_add_u32 s34, s48, 0x80000
	s_addc_u32 s35, s49, 0
	s_add_i32 s4, s4, s24
	global_load_lds_dwordx4 v2, s[48:49]
	s_mov_b32 m0, s4
	s_nop 0
	global_load_lds_dwordx4 v4, s[34:35]
	s_add_i32 m0, s4, 0x2000
	s_nop 0
	global_load_lds_dwordx4 v2, s[34:35]
	s_mov_b32 m0, s54
	s_nop 0
	global_load_lds_dwordx4 v170, s[52:53]
	s_mov_b32 m0, s55
	s_nop 0
	global_load_lds_dwordx4 v168, s[52:53]
	s_waitcnt vmcnt(8)
	s_waitcnt lgkmcnt(0)
	s_barrier
; #define PG8_STAGE(bufoff, gbase, voff) do { _Pragma("unroll") for (int _i = 0; _i < 2; ++_i) \
;         __builtin_amdgcn_global_load_lds((const unsigned*)((const char*)(gbase) + (voff)[_i]), (PG8_LAS unsigned*)(lds + (bufoff) + ldsw + _i * 8192), 16, 0, 0); } while (0)
; #define PG8_LDA(dst, b, h) do { _Pragma("unroll") for (int m = 0; m < 4; ++m) _Pragma("unroll") for (int k = 0; k < 2; ++k) dst[m][k] = *(const PG8_LAS bf16x8*)(lds + PG8_SA(b, h) + aoff + m * 2048 + k * 1024); } while (0)
; #define PG8_LDB(dst, b, h) do { _Pragma("unroll") for (int n = 0; n < 2; ++n) _Pragma("unroll") for (int k = 0; k < 2; ++k) dst[n][k] = *(const PG8_LAS bf16x8*)(lds + PG8_SB(b, h) + boff + n * 2048 + k * 1024); } while (0)
; #define PG8_MMA(ai, bj, At, Bt) do { __builtin_amdgcn_s_setprio(1); _Pragma("unroll") for (int m = 0; m < 4; ++m) _Pragma("unroll") for (int n = 0; n < 2; ++n) _Pragma("unroll") for (int k = 0; k < 2; ++k) \
;         acc[ai][bj][m][n] = __builtin_amdgcn_mfma_f32_16x16x32_bf16(Bt[n][k], At[m][k], acc[ai][bj][m][n], 0, 0, 0); __builtin_amdgcn_s_setprio(0); } while (0)
; #define PG8_WAIT_V(n) asm volatile("s_waitcnt vmcnt(" #n ")" ::: "memory")
; #define PG8_WAIT_L(n) asm volatile("s_waitcnt lgkmcnt(" #n ")" ::: "memory")
; #define PG8_BAR __builtin_amdgcn_s_barrier()
; #define PG8_SCHED __builtin_amdgcn_sched_barrier(0)
; template <class Epi, class Sched, bool ALIGN_EPI = false, bool SP2 = false>
; __device__ __forceinline__ void gemm_phase(PG8_LAS unsigned char* lds, const Gemm g, const Sched& S, const Epi& E) {
;     ...
;             PG8_WAIT_V(8); PG8_WAIT_L(0); PG8_BAR; PG8_MMA(1, 0, At, B0); PG8_MMA(1, 1, At, B1); PG8_BAR; PG8_SCHED;
;             PG8_LDB(B0, 1, 0); PG8_LDB(B1, 1, 1); PG8_SCHED; PG8_LDA(At, 1, 0); PG8_STAGE(PG8_SA(0, 1), a2 + hstep, voffA);
;             PG8_WAIT_V(8); PG8_WAIT_L(0); PG8_BAR; PG8_MMA(0, 0, At, B0); PG8_MMA(0, 1, At, B1); PG8_BAR; PG8_SCHED;
	v_mfma_f32_16x16x32_bf16 v[58:61], v[134:137], v[184:187], v[58:61]
	v_mfma_f32_16x16x32_bf16 v[58:61], v[138:141], v[190:193], v[58:61]
	v_mfma_f32_16x16x32_bf16 v[54:57], v[142:145], v[184:187], v[54:57]
	v_mfma_f32_16x16x32_bf16 v[54:57], v[146:149], v[190:193], v[54:57]
	v_mfma_f32_16x16x32_bf16 v[66:69], v[150:153], v[184:187], v[66:69]
	v_mfma_f32_16x16x32_bf16 v[66:69], v[154:157], v[190:193], v[66:69]
	v_mfma_f32_16x16x32_bf16 v[62:65], v[176:179], v[184:187], v[62:65]
	v_mfma_f32_16x16x32_bf16 v[62:65], v[180:183], v[190:193], v[62:65]
	v_mfma_f32_16x16x32_bf16 v[38:41], v[176:179], v[210:213], v[38:41]
	v_mfma_f32_16x16x32_bf16 v[38:41], v[180:183], v[214:217], v[38:41]
	v_mfma_f32_16x16x32_bf16 v[46:49], v[150:153], v[210:213], v[46:49]
	v_mfma_f32_16x16x32_bf16 v[46:49], v[154:157], v[214:217], v[46:49]
	v_mfma_f32_16x16x32_bf16 v[42:45], v[142:145], v[210:213], v[42:45]
	v_mfma_f32_16x16x32_bf16 v[42:45], v[146:149], v[214:217], v[42:45]
	v_mfma_f32_16x16x32_bf16 v[50:53], v[134:137], v[210:213], v[50:53]
	v_mfma_f32_16x16x32_bf16 v[50:53], v[138:141], v[214:217], v[50:53]
	v_mfma_f32_16x16x32_bf16 v[34:37], v[134:137], v[218:221], v[34:37]
	v_mfma_f32_16x16x32_bf16 v[34:37], v[138:141], v[222:225], v[34:37]
	v_mfma_f32_16x16x32_bf16 v[26:29], v[142:145], v[218:221], v[26:29]
	v_mfma_f32_16x16x32_bf16 v[26:29], v[146:149], v[222:225], v[26:29]
	v_mfma_f32_16x16x32_bf16 v[30:33], v[150:153], v[218:221], v[30:33]
	v_mfma_f32_16x16x32_bf16 v[30:33], v[154:157], v[222:225], v[30:33]
	v_mfma_f32_16x16x32_bf16 v[22:25], v[176:179], v[218:221], v[22:25]
	v_mfma_f32_16x16x32_bf16 v[22:25], v[180:183], v[222:225], v[22:25]
	v_mfma_f32_16x16x32_bf16 v[6:9], v[176:179], v[226:229], v[6:9]
	v_mfma_f32_16x16x32_bf16 v[6:9], v[180:183], v[230:233], v[6:9]
	v_mfma_f32_16x16x32_bf16 v[14:17], v[150:153], v[226:229], v[14:17]
	v_mfma_f32_16x16x32_bf16 v[14:17], v[154:157], v[230:233], v[14:17]
	v_mfma_f32_16x16x32_bf16 v[10:13], v[142:145], v[226:229], v[10:13]
	v_mfma_f32_16x16x32_bf16 v[10:13], v[146:149], v[230:233], v[10:13]
	v_mfma_f32_16x16x32_bf16 v[18:21], v[134:137], v[226:229], v[18:21]
	v_mfma_f32_16x16x32_bf16 v[18:21], v[138:141], v[230:233], v[18:21]
	s_barrier
	s_add_i32 s4, 0, 0x18000
	s_add_i32 s5, 0, 0x1c000
	ds_read_b128 v[134:137], v236
	ds_read_b128 v[138:141], v236 offset:1024
	ds_read_b128 v[142:145], v236 offset:2048
	ds_read_b128 v[146:149], v236 offset:3072
	ds_read_b128 v[150:153], v237
	ds_read_b128 v[154:157], v237 offset:1024
	ds_read_b128 v[176:179], v237 offset:2048
	ds_read_b128 v[180:183], v237 offset:3072
	s_add_u32 s34, s52, 0x80000
	s_addc_u32 s35, s53, 0
	s_mov_b32 m0, s56
	ds_read_b128 v[184:187], v188 offset:32768
	ds_read_b128 v[190:193], v188 offset:33792
	ds_read_b128 v[210:213], v188 offset:34816
	ds_read_b128 v[214:217], v188 offset:35840
	ds_read_b128 v[218:221], v188 offset:36864
	ds_read_b128 v[222:225], v188 offset:37888
	ds_read_b128 v[226:229], v188 offset:38912
	ds_read_b128 v[230:233], v188 offset:39936
	global_load_lds_dwordx4 v170, s[34:35]
	s_mov_b32 m0, s57
	s_nop 0
	global_load_lds_dwordx4 v168, s[34:35]
	s_waitcnt vmcnt(8)
	s_waitcnt lgkmcnt(0)
	s_barrier
	v_mfma_f32_16x16x32_bf16 v[122:125], v[134:137], v[184:187], v[122:125]
	v_mfma_f32_16x16x32_bf16 v[122:125], v[138:141], v[190:193], v[122:125]
	v_mfma_f32_16x16x32_bf16 v[118:121], v[142:145], v[184:187], v[118:121]
	v_mfma_f32_16x16x32_bf16 v[118:121], v[146:149], v[190:193], v[118:121]
	v_mfma_f32_16x16x32_bf16 v[130:133], v[150:153], v[184:187], v[130:133]
	v_mfma_f32_16x16x32_bf16 v[130:133], v[154:157], v[190:193], v[130:133]
	v_mfma_f32_16x16x32_bf16 v[126:129], v[176:179], v[184:187], v[126:129]
	v_mfma_f32_16x16x32_bf16 v[126:129], v[180:183], v[190:193], v[126:129]
	v_mfma_f32_16x16x32_bf16 v[102:105], v[176:179], v[210:213], v[102:105]
	v_mfma_f32_16x16x32_bf16 v[102:105], v[180:183], v[214:217], v[102:105]
	v_mfma_f32_16x16x32_bf16 v[110:113], v[150:153], v[210:213], v[110:113]
	v_mfma_f32_16x16x32_bf16 v[110:113], v[154:157], v[214:217], v[110:113]
	v_mfma_f32_16x16x32_bf16 v[106:109], v[142:145], v[210:213], v[106:109]
	v_mfma_f32_16x16x32_bf16 v[106:109], v[146:149], v[214:217], v[106:109]
	v_mfma_f32_16x16x32_bf16 v[114:117], v[134:137], v[210:213], v[114:117]
	v_mfma_f32_16x16x32_bf16 v[114:117], v[138:141], v[214:217], v[114:117]
	v_mfma_f32_16x16x32_bf16 v[98:101], v[134:137], v[218:221], v[98:101]
	v_mfma_f32_16x16x32_bf16 v[98:101], v[138:141], v[222:225], v[98:101]
	v_mfma_f32_16x16x32_bf16 v[90:93], v[142:145], v[218:221], v[90:93]
	v_mfma_f32_16x16x32_bf16 v[90:93], v[146:149], v[222:225], v[90:93]
	v_mfma_f32_16x16x32_bf16 v[94:97], v[150:153], v[218:221], v[94:97]
	v_mfma_f32_16x16x32_bf16 v[94:97], v[154:157], v[222:225], v[94:97]
	v_mfma_f32_16x16x32_bf16 v[86:89], v[176:179], v[218:221], v[86:89]
	v_mfma_f32_16x16x32_bf16 v[86:89], v[180:183], v[222:225], v[86:89]
	v_mfma_f32_16x16x32_bf16 v[70:73], v[176:179], v[226:229], v[70:73]
	v_mfma_f32_16x16x32_bf16 v[70:73], v[180:183], v[230:233], v[70:73]
	v_mfma_f32_16x16x32_bf16 v[78:81], v[150:153], v[226:229], v[78:81]
	v_mfma_f32_16x16x32_bf16 v[78:81], v[154:157], v[230:233], v[78:81]
	v_mfma_f32_16x16x32_bf16 v[74:77], v[142:145], v[226:229], v[74:77]
	v_mfma_f32_16x16x32_bf16 v[74:77], v[146:149], v[230:233], v[74:77]
	v_mfma_f32_16x16x32_bf16 v[82:85], v[134:137], v[226:229], v[82:85]
	v_mfma_f32_16x16x32_bf16 v[82:85], v[138:141], v[230:233], v[82:85]
	s_barrier
; #define PG8_STAGE(bufoff, gbase, voff) do { _Pragma("unroll") for (int _i = 0; _i < 2; ++_i) \
;         __builtin_amdgcn_global_load_lds((const unsigned*)((const char*)(gbase) + (voff)[_i]), (PG8_LAS unsigned*)(lds + (bufoff) + ldsw + _i * 8192), 16, 0, 0); } while (0)
; #define PG8_LDA(dst, b, h) do { _Pragma("unroll") for (int m = 0; m < 4; ++m) _Pragma("unroll") for (int k = 0; k < 2; ++k) dst[m][k] = *(const PG8_LAS bf16x8*)(lds + PG8_SA(b, h) + aoff + m * 2048 + k * 1024); } while (0)
; #define PG8_MMA(ai, bj, At, Bt) do { __builtin_amdgcn_s_setprio(1); _Pragma("unroll") for (int m = 0; m < 4; ++m) _Pragma("unroll") for (int n = 0; n < 2; ++n) _Pragma("unroll") for (int k = 0; k < 2; ++k) \
;         acc[ai][bj][m][n] = __builtin_amdgcn_mfma_f32_16x16x32_bf16(Bt[n][k], At[m][k], acc[ai][bj][m][n], 0, 0, 0); __builtin_amdgcn_s_setprio(0); } while (0)
; #define PG8_WAIT_V(n) asm volatile("s_waitcnt vmcnt(" #n ")" ::: "memory")
; #define PG8_WAIT_L(n) asm volatile("s_waitcnt lgkmcnt(" #n ")" ::: "memory")
; #define PG8_BAR __builtin_amdgcn_s_barrier()
; #define PG8_SCHED __builtin_amdgcn_sched_barrier(0)
; template <class Epi, class Sched, bool ALIGN_EPI = false, bool SP2 = false>
; __device__ __forceinline__ void gemm_phase(PG8_LAS unsigned char* lds, const Gemm g, const Sched& S, const Epi& E) {
;     ...
;         for (int t = 0; t < nt; t += 2) {
;     ...
;             PG8_LDA(At, 1, 1); PG8_STAGE(PG8_SB(1, 0), b3, voffB); PG8_STAGE(PG8_SB(1, 1), b3 + hstep, voffB); PG8_STAGE(PG8_SA(1, 0), a3, voffA);
;             PG8_WAIT_V(8); PG8_WAIT_L(0); PG8_BAR; PG8_MMA(1, 0, At, B0); PG8_MMA(1, 1, At, B1); PG8_BAR; PG8_SCHED;
	s_add_i32 s4, s4, s24
	s_add_i32 m0, s4, 0xffffff80
	ds_read_b128 v[184:187], v188 offset:49152
	ds_read_b128 v[190:193], v188 offset:50176
	ds_read_b128 v[210:213], v188 offset:51200
	ds_read_b128 v[214:217], v188 offset:52224
	ds_read_b128 v[218:221], v188 offset:53248
	ds_read_b128 v[222:225], v188 offset:54272
	ds_read_b128 v[226:229], v188 offset:55296
	ds_read_b128 v[230:233], v188 offset:56320
	global_load_lds_dwordx4 v4, s[48:49] offset:128
	s_add_i32 m0, s4, 0x1f80
	s_add_u32 s34, s48, 0x80080
	s_addc_u32 s35, s49, 0
	s_add_i32 s4, s5, s24
	global_load_lds_dwordx4 v2, s[48:49] offset:128
	s_mov_b32 m0, s4
	s_nop 0
	global_load_lds_dwordx4 v4, s[34:35]
	s_add_i32 m0, s4, 0x2000
	s_nop 0
	global_load_lds_dwordx4 v2, s[34:35]
	s_add_i32 m0, s60, 0xffffff80
	s_nop 0
	global_load_lds_dwordx4 v170, s[52:53] offset:128
	s_add_i32 m0, s61, 0xffffff80
	s_nop 0
	global_load_lds_dwordx4 v168, s[52:53] offset:128
	s_waitcnt vmcnt(8)
	s_waitcnt lgkmcnt(0)
	s_barrier
	v_mfma_f32_16x16x32_bf16 v[58:61], v[134:137], v[184:187], v[58:61]
	v_mfma_f32_16x16x32_bf16 v[58:61], v[138:141], v[190:193], v[58:61]
	v_mfma_f32_16x16x32_bf16 v[54:57], v[142:145], v[184:187], v[54:57]
	v_mfma_f32_16x16x32_bf16 v[54:57], v[146:149], v[190:193], v[54:57]
	v_mfma_f32_16x16x32_bf16 v[66:69], v[150:153], v[184:187], v[66:69]
	v_mfma_f32_16x16x32_bf16 v[66:69], v[154:157], v[190:193], v[66:69]
	v_mfma_f32_16x16x32_bf16 v[62:65], v[176:179], v[184:187], v[62:65]
	v_mfma_f32_16x16x32_bf16 v[62:65], v[180:183], v[190:193], v[62:65]
	v_mfma_f32_16x16x32_bf16 v[38:41], v[176:179], v[210:213], v[38:41]
	v_mfma_f32_16x16x32_bf16 v[38:41], v[180:183], v[214:217], v[38:41]
	v_mfma_f32_16x16x32_bf16 v[46:49], v[150:153], v[210:213], v[46:49]
	v_mfma_f32_16x16x32_bf16 v[46:49], v[154:157], v[214:217], v[46:49]
	v_mfma_f32_16x16x32_bf16 v[42:45], v[142:145], v[210:213], v[42:45]
	v_mfma_f32_16x16x32_bf16 v[42:45], v[146:149], v[214:217], v[42:45]
	v_mfma_f32_16x16x32_bf16 v[50:53], v[134:137], v[210:213], v[50:53]
	v_mfma_f32_16x16x32_bf16 v[50:53], v[138:141], v[214:217], v[50:53]
	v_mfma_f32_16x16x32_bf16 v[34:37], v[134:137], v[218:221], v[34:37]
	v_mfma_f32_16x16x32_bf16 v[34:37], v[138:141], v[222:225], v[34:37]
	v_mfma_f32_16x16x32_bf16 v[26:29], v[142:145], v[218:221], v[26:29]
	v_mfma_f32_16x16x32_bf16 v[26:29], v[146:149], v[222:225], v[26:29]
	v_mfma_f32_16x16x32_bf16 v[30:33], v[150:153], v[218:221], v[30:33]
	v_mfma_f32_16x16x32_bf16 v[30:33], v[154:157], v[222:225], v[30:33]
	v_mfma_f32_16x16x32_bf16 v[22:25], v[176:179], v[218:221], v[22:25]
	v_mfma_f32_16x16x32_bf16 v[22:25], v[180:183], v[222:225], v[22:25]
	v_mfma_f32_16x16x32_bf16 v[6:9], v[176:179], v[226:229], v[6:9]
	v_mfma_f32_16x16x32_bf16 v[6:9], v[180:183], v[230:233], v[6:9]
	v_mfma_f32_16x16x32_bf16 v[14:17], v[150:153], v[226:229], v[14:17]
	v_mfma_f32_16x16x32_bf16 v[14:17], v[154:157], v[230:233], v[14:17]
	v_mfma_f32_16x16x32_bf16 v[10:13], v[142:145], v[226:229], v[10:13]
	v_mfma_f32_16x16x32_bf16 v[10:13], v[146:149], v[230:233], v[10:13]
	v_mfma_f32_16x16x32_bf16 v[18:21], v[134:137], v[226:229], v[18:21]
	v_mfma_f32_16x16x32_bf16 v[18:21], v[138:141], v[230:233], v[18:21]
	s_barrier
	s_add_i32 s20, s20, 2
	s_add_u32 s50, s50, 0x100
	s_addc_u32 s51, s51, 0
	s_add_u32 s69, s69, 0x100
	s_addc_u32 s71, s71, 0
	s_cmp_gt_u32 s20, 29
	s_cbranch_scc0 .LBB0_1738
	s_and_b64 vcc, exec, s[40:41]
	s_cbranch_vccz .LBB0_1741
	s_barrier
